# ping-pong attention loop: lazy softmax reference folded into QK accumulator init, staging moved to softmax segment, softmax segment at raised priority
# speedup vs baseline: 1.1032x; 1.0264x over previous
; __device__ __forceinline__ int swap23(int p) { return (p & ~12) | ((p & 4) << 1) | ((p & 8) >> 1); }
; #define A_STORE(buf) do { LAS unsigned char* bb = lds + (buf) * ABUF; \
;         *(LAS u32x4*)(bb + kr1 * KT_PITCH + kc1 * 16) = st[0]; *(LAS u32x4*)(bb + kr2 * KT_PITCH + kc2 * 16) = st[1]; *(LAS u32x4*)(bb + kr3 * KT_PITCH + kc3 * 16) = st[2]; \
;         *(LAS u32x4*)(bb + KT_BYTES + vd1 * VT_PITCH + vc * 16) = st[3]; *(LAS u32x4*)(bb + KT_BYTES + vd2 * VT_PITCH + vc * 16) = st[4]; } while (0)
; __device__ __forceinline__ void attn_unit(KParams& P, int l, const AUnit& U, LAS unsigned char* lds) {
;     ...
;     const int kr1 = tid / 20, kc1 = tid % 20, kr2 = (tid + 512) / 20, kc2 = (tid + 512) % 20, kr3 = ((tid & 255) + 1024) / 20, kc3 = ((tid & 255) + 1024) % 20;
;     const int vd1 = tid >> 3, vc = tid & 7, vd2 = vd1 + 64;
;     ...
;     A_LOAD(0); A_STORE(0);
;     __syncthreads();
;     f32x16 o[4];
; #pragma unroll
;     for (int d = 0; d < 4; ++d)
; #pragma unroll
;         for (int r = 0; r < 16; ++r) o[d][r] = 0.f;
;     float mrun = -1e30f, lrun = 0.f;
;     const int koff = swap23(i) * KT_PITCH + 16 * hi, voff = KT_BYTES + i * VT_PITCH + 16 * hi;
;     for (int t = 0; t < U.nt; ++t) {
;         const bool more = t + 1 < U.nt;
;         if (more) A_LOAD(t + 1);
.LBB0_677:
	s_or_b64 exec, exec, s[10:11]
	s_mov_b32 s3, 0x66666667
	v_mul_hi_i32 v1, v0, s3
	v_lshrrev_b32_e32 v2, 31, v1
	v_ashrrev_i32_e32 v1, 3, v1
	v_add_u32_e32 v1, v1, v2
	v_mul_lo_u32 v2, v1, 20
	v_sub_u32_e32 v16, v0, v2
	v_add_u32_e32 v2, 0x200, v0
	v_mul_hi_i32 v3, v2, s3
	v_lshrrev_b32_e32 v4, 31, v3
	v_ashrrev_i32_e32 v3, 3, v3
	v_add_u32_e32 v17, v3, v4
	v_mul_lo_u32 v3, v17, 20
	v_sub_u32_e32 v18, v2, v3
	s_movk_i32 s3, 0x400
	v_mov_b32_e32 v2, 0xff
	v_bitop3_b16 v2, v0, s3, v2 bitop3:0xec
	s_mov_b32 s3, 0xcccd
	v_mul_u32_u24_sdwa v3, v2, s3 dst_sel:DWORD dst_unused:UNUSED_PAD src0_sel:WORD_0 src1_sel:DWORD
	v_lshrrev_b32_e32 v19, 20, v3
	v_mul_lo_u16_e32 v3, 20, v19
	s_movk_i32 s3, 0xa0
	v_sub_u16_e32 v14, v2, v3
	v_mul_lo_u32 v2, v1, s3
	v_ashrrev_i32_e32 v3, 31, v2
	v_lshlrev_b32_e32 v6, 3, v16
	v_mul_lo_u32 v8, v17, s3
	v_lshlrev_b64 v[2:3], 1, v[2:3]
	v_ashrrev_i32_e32 v7, 31, v6
	v_ashrrev_i32_e32 v9, 31, v8
	v_lshlrev_b32_e32 v12, 3, v18
	v_lshl_add_u64 v[4:5], s[0:1], 0, v[2:3]
	v_lshlrev_b64 v[6:7], 1, v[6:7]
	v_lshlrev_b64 v[8:9], 1, v[8:9]
	v_ashrrev_i32_e32 v13, 31, v12
	v_lshl_add_u64 v[4:5], v[4:5], 0, v[6:7]
	v_lshl_add_u64 v[10:11], s[0:1], 0, v[8:9]
	v_lshlrev_b64 v[12:13], 1, v[12:13]
	v_lshl_add_u64 v[10:11], v[10:11], 0, v[12:13]
	global_load_dwordx4 v[136:139], v[4:5], off
	global_load_dwordx4 v[140:143], v[10:11], off
	v_mul_u32_u24_e32 v4, 0xa0, v19
	v_lshlrev_b32_e32 v4, 1, v4
	v_mov_b32_e32 v5, v157
	v_lshl_add_u64 v[10:11], s[0:1], 0, v[4:5]
	v_lshlrev_b32_e32 v166, 4, v14
	v_mov_b32_e32 v167, v157
	v_ashrrev_i32_e32 v20, 3, v0
	v_lshl_add_u64 v[10:11], v[10:11], 0, v[166:167]
	v_add_u32_e32 v21, 64, v20
	global_load_dwordx4 v[144:147], v[10:11], off
	v_mad_i64_i32 v[10:11], s[10:11], s8, v20, 0
	v_lshlrev_b32_e32 v14, 4, v0
	v_lshl_add_u64 v[10:11], v[10:11], 1, s[6:7]
	v_and_b32_e32 v168, 0x70, v14
	v_mov_b32_e32 v169, v157
	v_mad_i64_i32 v[14:15], s[10:11], s8, v21, 0
	v_lshl_add_u64 v[10:11], v[10:11], 0, v[168:169]
	v_lshl_add_u64 v[14:15], v[14:15], 1, s[6:7]
	v_lshl_add_u64 v[14:15], v[14:15], 0, v[168:169]
	global_load_dwordx4 v[148:151], v[10:11], off
	global_load_dwordx4 v[152:155], v[14:15], off
	v_and_b32_e32 v10, 19, v0
	v_lshlrev_b32_e32 v11, 1, v181
	v_lshrrev_b32_e32 v0, 1, v0
	s_add_u32 s6, s6, 0x80
	s_movk_i32 s3, 0x90
	v_mul_lo_u32 v184, v20, s3
	v_and_b32_e32 v11, 8, v11
	v_and_b32_e32 v0, 4, v0
	s_addc_u32 s7, s7, 0
	s_lshl_b32 s3, s8, 1
	s_movk_i32 s8, 0x150
	v_or3_b32 v0, v10, v11, v0
	v_mul_lo_u32 v186, v1, s8
	v_lshlrev_b32_e32 v190, 4, v16
	v_mul_u32_u24_e32 v187, 0x150, v0
	v_mul_lo_u32 v189, v17, s8
	v_add_u32_e32 v0, v186, v190
	v_lshlrev_b32_e32 v191, 4, v18
	v_mad_u32_u24 v1, v19, s8, v166
	v_add_u32_e32 v14, v184, v168
	v_add_u32_e32 v10, v189, v191
	v_mov_b32_e32 v32, v157
	v_mov_b32_e32 v33, v157
	v_mov_b32_e32 v46, v157
	v_mov_b32_e32 v47, v157
	v_mul_u32_u24_e32 v188, 0x150, v19
	v_mov_b32_e32 v34, v157
	v_mov_b32_e32 v35, v157
	v_mov_b32_e32 v36, v157
	v_mov_b32_e32 v37, v157
	v_mov_b32_e32 v38, v157
	v_mov_b32_e32 v39, v157
	v_mov_b32_e32 v40, v157
	v_mov_b32_e32 v41, v157
	v_mov_b32_e32 v42, v157
	v_mov_b32_e32 v43, v157
	v_mov_b32_e32 v44, v157
	v_mov_b32_e32 v45, v157
	v_mov_b64_e32 v[62:63], v[46:47]
	v_ashrrev_i32_e32 v163, 31, v162
	v_lshlrev_b32_e32 v164, 3, v183
	v_mul_u32_u24_e32 v165, 0x90, v181
	v_add_u32_e32 v185, 0x2400, v184
	v_mov_b64_e32 v[60:61], v[44:45]
	v_mov_b64_e32 v[58:59], v[42:43]
	s_waitcnt vmcnt(4)
	ds_write_b128 v0, v[136:139]
	s_waitcnt vmcnt(3)
	ds_write_b128 v10, v[140:143]
	s_waitcnt vmcnt(2)
	ds_write_b128 v1, v[144:147]
	s_waitcnt vmcnt(1)
	ds_write_b128 v14, v[148:151] offset:21504
	s_waitcnt vmcnt(0)
	ds_write_b128 v14, v[152:155] offset:30720
	v_mad_i64_i32 v[0:1], s[8:9], s3, v20, v[168:169]
	v_lshl_add_u64 v[170:171], s[6:7], 0, v[0:1]
	v_mad_i64_i32 v[0:1], s[8:9], s3, v21, v[168:169]
	v_lshl_add_u64 v[172:173], s[6:7], 0, v[0:1]
	v_lshl_add_u64 v[0:1], v[2:3], 0, v[6:7]
	s_mov_b64 s[6:7], 0x5000
	v_lshl_add_u64 v[174:175], v[0:1], 0, s[6:7]
	v_lshl_add_u64 v[0:1], v[8:9], 0, v[12:13]
	v_lshl_add_u64 v[176:177], v[0:1], 0, s[6:7]
	v_lshl_add_u64 v[0:1], v[4:5], 0, v[166:167]
	v_lshl_add_u64 v[178:179], v[0:1], 0, s[6:7]
	v_mov_b64_e32 v[16:17], v[32:33]
	v_mov_b64_e32 v[0:1], v[32:33]
	s_lshl_b32 s3, s89, 6
	s_mov_b32 s6, 0
	v_mov_b32_e32 v169, 0xf149f2ca
	v_mov_b32_e32 v167, 0
	v_mov_b64_e32 v[56:57], v[40:41]
	v_mov_b64_e32 v[54:55], v[38:39]
	v_mov_b64_e32 v[52:53], v[36:37]
	v_mov_b64_e32 v[50:51], v[34:35]
	v_mov_b64_e32 v[48:49], v[32:33]
	v_mov_b64_e32 v[18:19], v[34:35]
	v_mov_b64_e32 v[20:21], v[36:37]
	v_mov_b64_e32 v[22:23], v[38:39]
	v_mov_b64_e32 v[24:25], v[40:41]
	v_mov_b64_e32 v[26:27], v[42:43]
	v_mov_b64_e32 v[28:29], v[44:45]
	v_mov_b64_e32 v[30:31], v[46:47]
	v_mov_b64_e32 v[2:3], v[34:35]
	v_mov_b64_e32 v[4:5], v[36:37]
	v_mov_b64_e32 v[6:7], v[38:39]
	v_mov_b64_e32 v[8:9], v[40:41]
	v_mov_b64_e32 v[10:11], v[42:43]
	v_mov_b64_e32 v[12:13], v[44:45]
	v_mov_b64_e32 v[14:15], v[46:47]
	s_mov_b32 s7, 0
	v_lshl_add_u64 v[174:175], s[0:1], 0, v[174:175]
	v_lshl_add_u64 v[176:177], s[0:1], 0, v[176:177]
	v_lshl_add_u64 v[178:179], s[0:1], 0, v[178:179]
	s_mov_b64 s[26:27], 0x5000
	v_add_u32_e32 v216, v186, v190
	v_add_u32_e32 v217, v189, v191
	v_add_u32_e32 v218, v188, v166
	v_add_u32_e32 v219, v184, v168
	v_add_u32_e32 v220, v185, v168
	v_mov_b32_e32 v169, 0
	v_mov_b32_e32 v232, 0
	v_mov_b32_e32 v233, 0
	v_mov_b32_e32 v234, 0
	v_mov_b32_e32 v235, 0
	v_mov_b32_e32 v236, 0
	v_mov_b32_e32 v237, 0
	v_mov_b32_e32 v238, 0
	v_mov_b32_e32 v239, 0
	v_mov_b32_e32 v240, 0
	v_mov_b32_e32 v241, 0
	v_mov_b32_e32 v242, 0
	v_mov_b32_e32 v243, 0
	v_mov_b32_e32 v244, 0
	v_mov_b32_e32 v245, 0
	v_mov_b32_e32 v246, 0
	v_mov_b32_e32 v247, 0
	s_mov_b32 s20, 0
	s_mov_b32 s22, 0
	s_mov_b32 s23, 0x9c00
	s_mov_b32 s24, 0x13800
	s_cmp_gt_u32 s89, 1
	s_cbranch_scc0 .Lattn_pro_noload
	global_load_dwordx4 v[136:139], v[174:175], off
	global_load_dwordx4 v[140:143], v[176:177], off
	global_load_dwordx4 v[144:147], v[178:179], off
	global_load_dwordx4 v[148:151], v[170:171], off
	global_load_dwordx4 v[152:155], v[172:173], off
	v_lshl_add_u64 v[174:175], v[174:175], 0, s[26:27]
	v_lshl_add_u64 v[176:177], v[176:177], 0, s[26:27]
	v_lshl_add_u64 v[178:179], v[178:179], 0, s[26:27]
	v_lshl_add_u64 v[170:171], v[170:171], 0, s[82:83]
	v_lshl_add_u64 v[172:173], v[172:173], 0, s[82:83]
; __device__ __forceinline__ int swap23(int p) { return (p & ~12) | ((p & 4) << 1) | ((p & 8) >> 1); }
; #define A_STORE(buf) do { LAS unsigned char* bb = lds + (buf) * ABUF; \
;         *(LAS u32x4*)(bb + kr1 * KT_PITCH + kc1 * 16) = st[0]; *(LAS u32x4*)(bb + kr2 * KT_PITCH + kc2 * 16) = st[1]; *(LAS u32x4*)(bb + kr3 * KT_PITCH + kc3 * 16) = st[2]; \
;         *(LAS u32x4*)(bb + KT_BYTES + vd1 * VT_PITCH + vc * 16) = st[3]; *(LAS u32x4*)(bb + KT_BYTES + vd2 * VT_PITCH + vc * 16) = st[4]; } while (0)
; __device__ __forceinline__ void attn_unit(KParams& P, int l, const AUnit& U, LAS unsigned char* lds) {
;     ...
;     A_LOAD(0); A_STORE(0);
;     __syncthreads();
;     f32x16 o[4];
; #pragma unroll
;     for (int d = 0; d < 4; ++d)
; #pragma unroll
;         for (int r = 0; r < 16; ++r) o[d][r] = 0.f;
;     float mrun = -1e30f, lrun = 0.f;
;     const int koff = swap23(i) * KT_PITCH + 16 * hi, voff = KT_BYTES + i * VT_PITCH + 16 * hi;
;     for (int t = 0; t < U.nt; ++t) {
;         const bool more = t + 1 < U.nt;
;         if (more) A_LOAD(t + 1);
.Lattn_pro_noload:
	s_waitcnt lgkmcnt(0)
	s_barrier
	s_cmp_lt_u32 s88, 4
	s_cbranch_scc1 .Lattn_x0
	s_mov_b32 s29, 0x9c00
	s_mov_b32 s30, 2
	s_waitcnt vmcnt(0)
	v_add_u32_e32 v221, s29, v216
	ds_write_b128 v221, v[136:139]
	v_add_u32_e32 v221, s29, v217
	ds_write_b128 v221, v[140:143]
	v_add_u32_e32 v221, s29, v218
	ds_write_b128 v221, v[144:147]
	v_add_u32_e32 v221, s29, v219
	ds_write_b128 v221, v[148:151] offset:21504
	v_add_u32_e32 v221, s29, v220
	ds_write_b128 v221, v[152:155] offset:21504
	s_cmp_lt_u32 s30, s89
	s_cbranch_scc0 .Lattn_noload_entry
	global_load_dwordx4 v[136:139], v[174:175], off
	global_load_dwordx4 v[140:143], v[176:177], off
	global_load_dwordx4 v[144:147], v[178:179], off
	global_load_dwordx4 v[148:151], v[170:171], off
	global_load_dwordx4 v[152:155], v[172:173], off
	v_lshl_add_u64 v[174:175], v[174:175], 0, s[26:27]
	v_lshl_add_u64 v[176:177], v[176:177], 0, s[26:27]
	v_lshl_add_u64 v[178:179], v[178:179], 0, s[26:27]
	v_lshl_add_u64 v[170:171], v[170:171], 0, s[82:83]
	v_lshl_add_u64 v[172:173], v[172:173], 0, s[82:83]

; #define LAS __attribute__((address_space(3)))
; __device__ __forceinline__ void attn_unit(KParams& P, int l, const AUnit& U, LAS unsigned char* lds) {
;     ...
;     for (int t = 0; t < U.nt; ++t) {
;         const bool more = t + 1 < U.nt;
;         if (more) A_LOAD(t + 1);
;         const LAS unsigned char* bb = lds + (t & 1) * ABUF;
;         f32x16 p0, p1;
; #pragma unroll
;         for (int r = 0; r < 16; ++r) { p0[r] = 0.f; p1[r] = 0.f; }
; #pragma unroll
;         for (int s = 0; s < 10; ++s) {
;             const bf16x8 k0 = *(const LAS bf16x8*)(bb + koff + 32 * s), k1 = *(const LAS bf16x8*)(bb + koff + 32 * KT_PITCH + 32 * s);
;             p0 = __builtin_amdgcn_mfma_f32_32x32x16_bf16(k0, qf[s], p0, 0, 0, 0);
;             p1 = __builtin_amdgcn_mfma_f32_32x32x16_bf16(k1, qf[s], p1, 0, 0, 0);
;         }
;         if ((t + 1) * 64 > U.kvlen) {
;             const int kb0 = t * 64 + 8 * hi;
; #pragma unroll
;             for (int r = 0; r < 16; ++r) { const int kv = kb0 + 16 * (r >> 3) + (r & 7); if (kv >= U.kvlen) p0[r] = -INFINITY; if (kv + 32 >= U.kvlen) p1[r] = -INFINITY; }
.Lattn_x0:
	s_mov_b32 s23, 0
	s_mov_b32 s24, 0x9c00
	v_add3_u32 v230, s23, v187, v156
	ds_read_b128 v[192:195], v230
	ds_read_b128 v[196:199], v230 offset:10752
	ds_read_b128 v[200:203], v230 offset:32
	ds_read_b128 v[204:207], v230 offset:10784
	ds_read_b128 v[208:211], v230 offset:64
	ds_read_b128 v[226:229], v230 offset:10816
	s_waitcnt lgkmcnt(5)
	v_mfma_f32_32x32x16_bf16 v[80:95], v[192:195], v[96:99], v[232:247]
	ds_read_b128 v[248:251], v230 offset:96
	s_waitcnt lgkmcnt(5)
	v_mfma_f32_32x32x16_bf16 v[64:79], v[196:199], v[96:99], v[232:247]
	ds_read_b128 v[192:195], v230 offset:10848
	s_waitcnt lgkmcnt(5)
	v_mfma_f32_32x32x16_bf16 v[80:95], v[200:203], v[100:103], v[80:95]
	ds_read_b128 v[196:199], v230 offset:128
	s_waitcnt lgkmcnt(5)
	v_mfma_f32_32x32x16_bf16 v[64:79], v[204:207], v[100:103], v[64:79]
	ds_read_b128 v[200:203], v230 offset:10880
	s_waitcnt lgkmcnt(5)
	v_mfma_f32_32x32x16_bf16 v[80:95], v[208:211], v[104:107], v[80:95]
	ds_read_b128 v[204:207], v230 offset:160
	s_waitcnt lgkmcnt(5)
	v_mfma_f32_32x32x16_bf16 v[64:79], v[226:229], v[104:107], v[64:79]
	ds_read_b128 v[208:211], v230 offset:10912
	s_waitcnt lgkmcnt(5)
	v_mfma_f32_32x32x16_bf16 v[80:95], v[248:251], v[108:111], v[80:95]
	ds_read_b128 v[226:229], v230 offset:192
	s_waitcnt lgkmcnt(5)
	v_mfma_f32_32x32x16_bf16 v[64:79], v[192:195], v[108:111], v[64:79]
	ds_read_b128 v[248:251], v230 offset:10944
	s_waitcnt lgkmcnt(5)
	v_mfma_f32_32x32x16_bf16 v[80:95], v[196:199], v[112:115], v[80:95]
	ds_read_b128 v[192:195], v230 offset:224
	s_waitcnt lgkmcnt(5)
	v_mfma_f32_32x32x16_bf16 v[64:79], v[200:203], v[112:115], v[64:79]
	ds_read_b128 v[196:199], v230 offset:10976
	s_waitcnt lgkmcnt(5)
	v_mfma_f32_32x32x16_bf16 v[80:95], v[204:207], v[116:119], v[80:95]
	ds_read_b128 v[200:203], v230 offset:256
	s_waitcnt lgkmcnt(5)
	v_mfma_f32_32x32x16_bf16 v[64:79], v[208:211], v[116:119], v[64:79]
	ds_read_b128 v[204:207], v230 offset:11008
	s_waitcnt lgkmcnt(5)
	v_mfma_f32_32x32x16_bf16 v[80:95], v[226:229], v[120:123], v[80:95]
	ds_read_b128 v[208:211], v230 offset:288
	s_waitcnt lgkmcnt(5)
	v_mfma_f32_32x32x16_bf16 v[64:79], v[248:251], v[120:123], v[64:79]
	ds_read_b128 v[226:229], v230 offset:11040
	s_waitcnt lgkmcnt(5)
	v_mfma_f32_32x32x16_bf16 v[80:95], v[192:195], v[124:127], v[80:95]
	s_waitcnt lgkmcnt(4)
	v_mfma_f32_32x32x16_bf16 v[64:79], v[196:199], v[124:127], v[64:79]
	s_waitcnt lgkmcnt(3)
	v_mfma_f32_32x32x16_bf16 v[80:95], v[200:203], v[128:131], v[80:95]
	s_waitcnt lgkmcnt(2)
	v_mfma_f32_32x32x16_bf16 v[64:79], v[204:207], v[128:131], v[64:79]
	s_waitcnt lgkmcnt(1)
	v_mfma_f32_32x32x16_bf16 v[80:95], v[208:211], v[132:135], v[80:95]
	s_waitcnt lgkmcnt(0)
	v_mfma_f32_32x32x16_bf16 v[64:79], v[226:229], v[132:135], v[64:79]
	s_waitcnt lgkmcnt(0)
	s_mov_b32 s22, 0
	s_mov_b32 s23, 0x9c00
	s_mov_b32 s24, 0x13800
.Lattn_loop:
	s_barrier
	s_setprio 2
	s_nop 15
	s_nop 3
	s_lshl_b32 s25, s20, 6
	s_add_i32 s28, s25, 64
	s_cmp_le_u32 s28, s70
	s_cbranch_scc1 .Lattn_nomask
	v_add_u32_e32 v208, s25, v164
	v_add_u32_e32 v209, 0, v208
	v_cmp_gt_u32_e32 vcc, s70, v209
	v_cndmask_b32_e32 v80, v225, v80, vcc
	v_add_u32_e32 v209, 32, v208
	v_cmp_gt_u32_e32 vcc, s70, v209
	v_cndmask_b32_e32 v64, v225, v64, vcc
	v_add_u32_e32 v209, 1, v208
	v_cmp_gt_u32_e32 vcc, s70, v209
	v_cndmask_b32_e32 v81, v225, v81, vcc
	v_add_u32_e32 v209, 33, v208
	v_cmp_gt_u32_e32 vcc, s70, v209
	v_cndmask_b32_e32 v65, v225, v65, vcc
	v_add_u32_e32 v209, 2, v208
	v_cmp_gt_u32_e32 vcc, s70, v209
	v_cndmask_b32_e32 v82, v225, v82, vcc
	v_add_u32_e32 v209, 34, v208
	v_cmp_gt_u32_e32 vcc, s70, v209
	v_cndmask_b32_e32 v66, v225, v66, vcc
	v_add_u32_e32 v209, 3, v208
	v_cmp_gt_u32_e32 vcc, s70, v209
	v_cndmask_b32_e32 v83, v225, v83, vcc
	v_add_u32_e32 v209, 35, v208
	v_cmp_gt_u32_e32 vcc, s70, v209
	v_cndmask_b32_e32 v67, v225, v67, vcc
	v_add_u32_e32 v209, 4, v208
	v_cmp_gt_u32_e32 vcc, s70, v209
	v_cndmask_b32_e32 v84, v225, v84, vcc
	v_add_u32_e32 v209, 36, v208
	v_cmp_gt_u32_e32 vcc, s70, v209
	v_cndmask_b32_e32 v68, v225, v68, vcc
	v_add_u32_e32 v209, 5, v208
	v_cmp_gt_u32_e32 vcc, s70, v209
	v_cndmask_b32_e32 v85, v225, v85, vcc
	v_add_u32_e32 v209, 37, v208
	v_cmp_gt_u32_e32 vcc, s70, v209
	v_cndmask_b32_e32 v69, v225, v69, vcc
	v_add_u32_e32 v209, 6, v208
	v_cmp_gt_u32_e32 vcc, s70, v209
	v_cndmask_b32_e32 v86, v225, v86, vcc
	v_add_u32_e32 v209, 38, v208
	v_cmp_gt_u32_e32 vcc, s70, v209
	v_cndmask_b32_e32 v70, v225, v70, vcc
	v_add_u32_e32 v209, 7, v208
	v_cmp_gt_u32_e32 vcc, s70, v209
	v_cndmask_b32_e32 v87, v225, v87, vcc
	v_add_u32_e32 v209, 39, v208
	v_cmp_gt_u32_e32 vcc, s70, v209
	v_cndmask_b32_e32 v71, v225, v71, vcc
	v_add_u32_e32 v209, 16, v208
	v_cmp_gt_u32_e32 vcc, s70, v209
	v_cndmask_b32_e32 v88, v225, v88, vcc
	v_add_u32_e32 v209, 48, v208
	v_cmp_gt_u32_e32 vcc, s70, v209
	v_cndmask_b32_e32 v72, v225, v72, vcc
	v_add_u32_e32 v209, 17, v208
	v_cmp_gt_u32_e32 vcc, s70, v209
	v_cndmask_b32_e32 v89, v225, v89, vcc
	v_add_u32_e32 v209, 49, v208
	v_cmp_gt_u32_e32 vcc, s70, v209
	v_cndmask_b32_e32 v73, v225, v73, vcc
	v_add_u32_e32 v209, 18, v208
	v_cmp_gt_u32_e32 vcc, s70, v209
	v_cndmask_b32_e32 v90, v225, v90, vcc
	v_add_u32_e32 v209, 50, v208
	v_cmp_gt_u32_e32 vcc, s70, v209
	v_cndmask_b32_e32 v74, v225, v74, vcc
	v_add_u32_e32 v209, 19, v208
	v_cmp_gt_u32_e32 vcc, s70, v209
	v_cndmask_b32_e32 v91, v225, v91, vcc
	v_add_u32_e32 v209, 51, v208
	v_cmp_gt_u32_e32 vcc, s70, v209
	v_cndmask_b32_e32 v75, v225, v75, vcc
	v_add_u32_e32 v209, 20, v208
	v_cmp_gt_u32_e32 vcc, s70, v209
	v_cndmask_b32_e32 v92, v225, v92, vcc
	v_add_u32_e32 v209, 52, v208
	v_cmp_gt_u32_e32 vcc, s70, v209
	v_cndmask_b32_e32 v76, v225, v76, vcc
	v_add_u32_e32 v209, 21, v208
	v_cmp_gt_u32_e32 vcc, s70, v209
	v_cndmask_b32_e32 v93, v225, v93, vcc
	v_add_u32_e32 v209, 53, v208
	v_cmp_gt_u32_e32 vcc, s70, v209
	v_cndmask_b32_e32 v77, v225, v77, vcc
	v_add_u32_e32 v209, 22, v208
	v_cmp_gt_u32_e32 vcc, s70, v209
	v_cndmask_b32_e32 v94, v225, v94, vcc
	v_add_u32_e32 v209, 54, v208
	v_cmp_gt_u32_e32 vcc, s70, v209
	v_cndmask_b32_e32 v78, v225, v78, vcc
	v_add_u32_e32 v209, 23, v208
	v_cmp_gt_u32_e32 vcc, s70, v209
	v_cndmask_b32_e32 v95, v225, v95, vcc
	v_add_u32_e32 v209, 55, v208
	v_cmp_gt_u32_e32 vcc, s70, v209
	v_cndmask_b32_e32 v79, v225, v79, vcc
; __device__ __forceinline__ void attn_unit(KParams& P, int l, const AUnit& U, LAS unsigned char* lds) {
;     ...
;         float mx = fmaxf(p0[0], p1[0]);
; #pragma unroll
;         for (int r = 1; r < 16; ++r) mx = fmaxf(mx, fmaxf(p0[r], p1[r]));
;         { const auto rr = __builtin_amdgcn_permlane32_swap(__float_as_uint(mx), __float_as_uint(mx), false, false);
;           mx = fmaxf(__uint_as_float(rr[0]), __uint_as_float(rr[1])); }
;         const float mnew = fmaxf(mrun, mx); const float f = __builtin_amdgcn_exp2f(mrun - mnew); const bool grew = __any(mnew > mrun); mrun = mnew;
;         f32x2 ps2 = {0.f, 0.f}; const f32x2 nm2 = {-mnew, -mnew};
; #pragma unroll
;         for (int r = 0; r < 16; r += 2) { f32x2 a = (f32x2){p0[r], p0[r + 1]} + nm2, b = (f32x2){p1[r], p1[r + 1]} + nm2;
;             a[0] = __builtin_amdgcn_exp2f(a[0]); a[1] = __builtin_amdgcn_exp2f(a[1]); b[0] = __builtin_amdgcn_exp2f(b[0]); b[1] = __builtin_amdgcn_exp2f(b[1]);
;             p0[r] = a[0]; p0[r + 1] = a[1]; p1[r] = b[0]; p1[r + 1] = b[1]; ps2 += a; ps2 += b; }
;         const float ps = ps2[0] + ps2[1];
;         lrun = lrun * f + ps;
;         if (grew) {
; #pragma unroll
;             for (int d = 0; d < 4; ++d)
; #pragma unroll
;                 for (int r = 0; r < 16; ++r) o[d][r] *= f;
;         }
.Lattn_nomask:
	v_max3_f32 v208, v80, v81, v82
	v_max3_f32 v209, v83, v84, v85
	v_max3_f32 v210, v86, v87, v88
	v_max3_f32 v211, v89, v90, v91
	v_max3_f32 v208, v208, v92, v93
	v_max3_f32 v209, v209, v94, v95
	v_max3_f32 v210, v210, v64, v65
	v_max3_f32 v211, v211, v66, v67
	v_max3_f32 v208, v208, v68, v69
	v_max3_f32 v209, v209, v70, v71
	v_max3_f32 v210, v210, v72, v73
	v_max3_f32 v211, v211, v74, v75
	v_max3_f32 v208, v208, v76, v77
	v_max3_f32 v209, v209, v78, v79
	v_max3_f32 v208, v208, v209, v210
	v_max_f32_e32 v208, v208, v211
	v_mov_b32_e32 v209, v208
	s_nop 1
	v_permlane32_swap_b32_e32 v208, v209
	v_max_f32_e32 v208, v208, v209
	s_cmp_eq_u32 s20, 0
	s_cbranch_scc1 .Lattn_first
	v_cmp_lt_f32_e32 vcc, 0x41000000, v208
	s_cbranch_vccz .Lattn_fast
	v_max_f32_e32 v180, 0, v208
	v_exp_f32_e64 v182, -v180
	s_nop 0
	v_pk_mul_f32 v[62:63], v[62:63], v[182:183] op_sel_hi:[1,0]
	v_pk_mul_f32 v[60:61], v[60:61], v[182:183] op_sel_hi:[1,0]
	v_pk_mul_f32 v[58:59], v[58:59], v[182:183] op_sel_hi:[1,0]
	v_pk_mul_f32 v[56:57], v[56:57], v[182:183] op_sel_hi:[1,0]
	v_pk_mul_f32 v[54:55], v[54:55], v[182:183] op_sel_hi:[1,0]
	v_pk_mul_f32 v[52:53], v[52:53], v[182:183] op_sel_hi:[1,0]
	v_pk_mul_f32 v[50:51], v[50:51], v[182:183] op_sel_hi:[1,0]
	v_pk_mul_f32 v[48:49], v[48:49], v[182:183] op_sel_hi:[1,0]
	v_pk_mul_f32 v[46:47], v[46:47], v[182:183] op_sel_hi:[1,0]
	v_pk_mul_f32 v[44:45], v[44:45], v[182:183] op_sel_hi:[1,0]
	v_pk_mul_f32 v[42:43], v[42:43], v[182:183] op_sel_hi:[1,0]
	v_pk_mul_f32 v[40:41], v[40:41], v[182:183] op_sel_hi:[1,0]
	v_pk_mul_f32 v[38:39], v[38:39], v[182:183] op_sel_hi:[1,0]
	v_pk_mul_f32 v[36:37], v[36:37], v[182:183] op_sel_hi:[1,0]
	v_pk_mul_f32 v[34:35], v[34:35], v[182:183] op_sel_hi:[1,0]
	v_pk_mul_f32 v[32:33], v[32:33], v[182:183] op_sel_hi:[1,0]
	v_pk_mul_f32 v[30:31], v[30:31], v[182:183] op_sel_hi:[1,0]
	v_pk_mul_f32 v[28:29], v[28:29], v[182:183] op_sel_hi:[1,0]
	v_pk_mul_f32 v[26:27], v[26:27], v[182:183] op_sel_hi:[1,0]
	v_pk_mul_f32 v[24:25], v[24:25], v[182:183] op_sel_hi:[1,0]
	v_pk_mul_f32 v[22:23], v[22:23], v[182:183] op_sel_hi:[1,0]
	v_pk_mul_f32 v[20:21], v[20:21], v[182:183] op_sel_hi:[1,0]
	v_pk_mul_f32 v[18:19], v[18:19], v[182:183] op_sel_hi:[1,0]
	v_pk_mul_f32 v[16:17], v[16:17], v[182:183] op_sel_hi:[1,0]
	v_pk_mul_f32 v[14:15], v[14:15], v[182:183] op_sel_hi:[1,0]
	v_pk_mul_f32 v[12:13], v[12:13], v[182:183] op_sel_hi:[1,0]
	v_pk_mul_f32 v[10:11], v[10:11], v[182:183] op_sel_hi:[1,0]
	v_pk_mul_f32 v[8:9], v[8:9], v[182:183] op_sel_hi:[1,0]
	v_pk_mul_f32 v[6:7], v[6:7], v[182:183] op_sel_hi:[1,0]
	v_pk_mul_f32 v[4:5], v[4:5], v[182:183] op_sel_hi:[1,0]
	v_pk_mul_f32 v[2:3], v[2:3], v[182:183] op_sel_hi:[1,0]
	v_pk_mul_f32 v[0:1], v[0:1], v[182:183] op_sel_hi:[1,0]
	v_mul_f32_e32 v167, v167, v182
	s_branch .Lattn_resc_common
.Lattn_first:
	v_mov_b32_e32 v180, v208
.Lattn_resc_common:
	v_sub_f32_e32 v80, v80, v180
	v_sub_f32_e32 v81, v81, v180
	v_sub_f32_e32 v82, v82, v180
	v_sub_f32_e32 v83, v83, v180
	v_sub_f32_e32 v84, v84, v180
	v_sub_f32_e32 v85, v85, v180
	v_sub_f32_e32 v86, v86, v180
	v_sub_f32_e32 v87, v87, v180
	v_sub_f32_e32 v88, v88, v180
	v_sub_f32_e32 v89, v89, v180
	v_sub_f32_e32 v90, v90, v180
	v_sub_f32_e32 v91, v91, v180
	v_sub_f32_e32 v92, v92, v180
	v_sub_f32_e32 v93, v93, v180
	v_sub_f32_e32 v94, v94, v180
	v_sub_f32_e32 v95, v95, v180
	v_sub_f32_e32 v64, v64, v180
	v_sub_f32_e32 v65, v65, v180
	v_sub_f32_e32 v66, v66, v180
	v_sub_f32_e32 v67, v67, v180
	v_sub_f32_e32 v68, v68, v180
	v_sub_f32_e32 v69, v69, v180
	v_sub_f32_e32 v70, v70, v180
	v_sub_f32_e32 v71, v71, v180
	v_sub_f32_e32 v72, v72, v180
	v_sub_f32_e32 v73, v73, v180
	v_sub_f32_e32 v74, v74, v180
	v_sub_f32_e32 v75, v75, v180
	v_sub_f32_e32 v76, v76, v180
	v_sub_f32_e32 v77, v77, v180
	v_sub_f32_e32 v78, v78, v180
	v_sub_f32_e32 v79, v79, v180
	v_add_f32_e32 v169, v169, v180
	v_xor_b32_e32 v232, 0x80000000, v169
	v_xor_b32_e32 v233, 0x80000000, v169
	v_xor_b32_e32 v234, 0x80000000, v169
	v_xor_b32_e32 v235, 0x80000000, v169
	v_xor_b32_e32 v236, 0x80000000, v169
	v_xor_b32_e32 v237, 0x80000000, v169
	v_xor_b32_e32 v238, 0x80000000, v169
	v_xor_b32_e32 v239, 0x80000000, v169
	v_xor_b32_e32 v240, 0x80000000, v169
	v_xor_b32_e32 v241, 0x80000000, v169
	v_xor_b32_e32 v242, 0x80000000, v169
	v_xor_b32_e32 v243, 0x80000000, v169
	v_xor_b32_e32 v244, 0x80000000, v169
	v_xor_b32_e32 v245, 0x80000000, v169
	v_xor_b32_e32 v246, 0x80000000, v169
	v_xor_b32_e32 v247, 0x80000000, v169
.Lattn_fast:
	s_cmp_lt_u32 s88, 4
	s_cselect_b32 s29, s23, s24
	s_cselect_b32 s30, 2, 3
	s_add_i32 s30, s30, s20
	s_waitcnt vmcnt(0)
	v_add_u32_e32 v221, s29, v216
	ds_write_b128 v221, v[136:139]
	v_add_u32_e32 v221, s29, v217
	ds_write_b128 v221, v[140:143]
	v_add_u32_e32 v221, s29, v218
	ds_write_b128 v221, v[144:147]
	v_add_u32_e32 v221, s29, v219
	ds_write_b128 v221, v[148:151] offset:21504
	v_add_u32_e32 v221, s29, v220
	ds_write_b128 v221, v[152:155] offset:21504
	s_cmp_lt_u32 s30, s89
	s_cbranch_scc0 .Lattn_noload_y
	global_load_dwordx4 v[136:139], v[174:175], off
	global_load_dwordx4 v[140:143], v[176:177], off
	global_load_dwordx4 v[144:147], v[178:179], off
	global_load_dwordx4 v[148:151], v[170:171], off
	global_load_dwordx4 v[152:155], v[172:173], off
	v_lshl_add_u64 v[174:175], v[174:175], 0, s[26:27]
	v_lshl_add_u64 v[176:177], v[176:177], 0, s[26:27]
	v_lshl_add_u64 v[178:179], v[178:179], 0, s[26:27]
	v_lshl_add_u64 v[170:171], v[170:171], 0, s[82:83]
	v_lshl_add_u64 v[172:173], v[172:173], 0, s[82:83]
; #define LAS __attribute__((address_space(3)))
; __device__ __forceinline__ unsigned cvt_pk_bf16(float lo, float hi) { f32x2 v = {lo, hi}; bf16x2_t b = __builtin_convertvector(v, bf16x2_t); return __builtin_bit_cast(unsigned, b); }
; __device__ __forceinline__ void attn_unit(KParams& P, int l, const AUnit& U, LAS unsigned char* lds) {
;     ...
;         const float mnew = fmaxf(mrun, mx); const float f = __builtin_amdgcn_exp2f(mrun - mnew); const bool grew = __any(mnew > mrun); mrun = mnew;
;         f32x2 ps2 = {0.f, 0.f}; const f32x2 nm2 = {-mnew, -mnew};
; #pragma unroll
;         for (int r = 0; r < 16; r += 2) { f32x2 a = (f32x2){p0[r], p0[r + 1]} + nm2, b = (f32x2){p1[r], p1[r + 1]} + nm2;
;             a[0] = __builtin_amdgcn_exp2f(a[0]); a[1] = __builtin_amdgcn_exp2f(a[1]); b[0] = __builtin_amdgcn_exp2f(b[0]); b[1] = __builtin_amdgcn_exp2f(b[1]);
;             p0[r] = a[0]; p0[r + 1] = a[1]; p1[r] = b[0]; p1[r + 1] = b[1]; ps2 += a; ps2 += b; }
;         const float ps = ps2[0] + ps2[1];
;         lrun = lrun * f + ps;
;         if (grew) {
; #pragma unroll
;             for (int d = 0; d < 4; ++d)
; #pragma unroll
;                 for (int r = 0; r < 16; ++r) o[d][r] *= f;
;         }
;         bf16x8 pf[4];
;         { u32x4 w;
;           w.x = cvt_pk_bf16(p0[0], p0[1]); w.y = cvt_pk_bf16(p0[2], p0[3]); w.z = cvt_pk_bf16(p0[4], p0[5]); w.w = cvt_pk_bf16(p0[6], p0[7]); pf[0] = __builtin_bit_cast(bf16x8, w);
;           w.x = cvt_pk_bf16(p0[8], p0[9]); w.y = cvt_pk_bf16(p0[10], p0[11]); w.z = cvt_pk_bf16(p0[12], p0[13]); w.w = cvt_pk_bf16(p0[14], p0[15]); pf[1] = __builtin_bit_cast(bf16x8, w);
;           w.x = cvt_pk_bf16(p1[0], p1[1]); w.y = cvt_pk_bf16(p1[2], p1[3]); w.z = cvt_pk_bf16(p1[4], p1[5]); w.w = cvt_pk_bf16(p1[6], p1[7]); pf[2] = __builtin_bit_cast(bf16x8, w);
;           w.x = cvt_pk_bf16(p1[8], p1[9]); w.y = cvt_pk_bf16(p1[10], p1[11]); w.z = cvt_pk_bf16(p1[12], p1[13]); w.w = cvt_pk_bf16(p1[14], p1[15]); pf[3] = __builtin_bit_cast(bf16x8, w); }
; #pragma unroll
;         for (int d = 0; d < 4; ++d)
; #pragma unroll
;             for (int ks = 0; ks < 4; ++ks) {
;                 const bf16x8 vf = *(const LAS bf16x8*)(bb + voff + d * 32 * VT_PITCH + 32 * ks);
.Lattn_noload_y:
	v_exp_f32_e32 v80, v80
	v_exp_f32_e32 v81, v81
	v_exp_f32_e32 v82, v82
	v_exp_f32_e32 v83, v83
	v_exp_f32_e32 v84, v84
	v_exp_f32_e32 v85, v85
	v_exp_f32_e32 v86, v86
	v_exp_f32_e32 v87, v87
	v_exp_f32_e32 v88, v88
	v_exp_f32_e32 v89, v89
	v_exp_f32_e32 v90, v90
	v_exp_f32_e32 v91, v91
	v_exp_f32_e32 v92, v92
	v_exp_f32_e32 v93, v93
	v_exp_f32_e32 v94, v94
	v_exp_f32_e32 v95, v95
	v_add_f32_e32 v208, v80, v81
	v_add_f32_e32 v208, v208, v82
	v_add_f32_e32 v208, v208, v83
	v_add_f32_e32 v208, v208, v84
	v_add_f32_e32 v208, v208, v85
	v_add_f32_e32 v208, v208, v86
	v_add_f32_e32 v208, v208, v87
	v_exp_f32_e32 v64, v64
	v_exp_f32_e32 v65, v65
	v_exp_f32_e32 v66, v66
	v_exp_f32_e32 v67, v67
	v_exp_f32_e32 v68, v68
	v_exp_f32_e32 v69, v69
	v_exp_f32_e32 v70, v70
	v_exp_f32_e32 v71, v71
	v_add_f32_e32 v209, v88, v89
	v_add_f32_e32 v209, v209, v90
	v_add_f32_e32 v209, v209, v91
	v_add_f32_e32 v209, v209, v92
	v_add_f32_e32 v209, v209, v93
	v_add_f32_e32 v209, v209, v94
	v_add_f32_e32 v209, v209, v95
	v_cvt_pk_bf16_f32 v80, v80, v81
	v_cvt_pk_bf16_f32 v81, v82, v83
	v_cvt_pk_bf16_f32 v82, v84, v85
	v_cvt_pk_bf16_f32 v83, v86, v87
	v_exp_f32_e32 v72, v72
	v_exp_f32_e32 v73, v73
	v_exp_f32_e32 v74, v74
	v_exp_f32_e32 v75, v75
	v_exp_f32_e32 v76, v76
	v_exp_f32_e32 v77, v77
	v_exp_f32_e32 v78, v78
	v_exp_f32_e32 v79, v79
	v_add_f32_e32 v210, v64, v65
	v_add_f32_e32 v210, v210, v66
	v_add_f32_e32 v210, v210, v67
	v_add_f32_e32 v210, v210, v68
	v_add_f32_e32 v210, v210, v69
	v_add_f32_e32 v210, v210, v70
	v_add_f32_e32 v210, v210, v71
	v_cvt_pk_bf16_f32 v84, v88, v89
	v_cvt_pk_bf16_f32 v85, v90, v91
	v_cvt_pk_bf16_f32 v86, v92, v93
	v_cvt_pk_bf16_f32 v87, v94, v95
	v_add_f32_e32 v211, v72, v73
	v_add_f32_e32 v211, v211, v74
	v_add_f32_e32 v211, v211, v75
	v_add_f32_e32 v211, v211, v76
	v_add_f32_e32 v211, v211, v77
	v_add_f32_e32 v211, v211, v78
	v_add_f32_e32 v211, v211, v79
	v_cvt_pk_bf16_f32 v64, v64, v65
	v_cvt_pk_bf16_f32 v65, v66, v67
	v_cvt_pk_bf16_f32 v66, v68, v69
	v_cvt_pk_bf16_f32 v67, v70, v71
	v_cvt_pk_bf16_f32 v68, v72, v73
	v_cvt_pk_bf16_f32 v69, v74, v75
	v_cvt_pk_bf16_f32 v70, v76, v77
	v_cvt_pk_bf16_f32 v71, v78, v79
	v_add_f32_e32 v208, v208, v209
	v_add_f32_e32 v210, v210, v211
	v_add_f32_e32 v208, v208, v210
	v_add_f32_e32 v167, v167, v208
	s_waitcnt lgkmcnt(0)
	v_add3_u32 v231, s22, v165, v156
	ds_read_b128 v[192:195], v231 offset:21504
	ds_read_b128 v[196:199], v231 offset:21536
	ds_read_b128 v[200:203], v231 offset:21568
	ds_read_b128 v[204:207], v231 offset:21600
	ds_read_b128 v[208:211], v231 offset:26112
	ds_read_b128 v[226:229], v231 offset:26144
	s_setprio 0
	s_barrier
	s_add_i32 s25, s20, 1
	s_cmp_lt_u32 s25, s89
	s_cbranch_scc0 .Lattn_xlast
; #define LAS __attribute__((address_space(3)))
; #define A_STORE(buf) do { LAS unsigned char* bb = lds + (buf) * ABUF; \
;         *(LAS u32x4*)(bb + kr1 * KT_PITCH + kc1 * 16) = st[0]; *(LAS u32x4*)(bb + kr2 * KT_PITCH + kc2 * 16) = st[1]; *(LAS u32x4*)(bb + kr3 * KT_PITCH + kc3 * 16) = st[2]; \
;         *(LAS u32x4*)(bb + KT_BYTES + vd1 * VT_PITCH + vc * 16) = st[3]; *(LAS u32x4*)(bb + KT_BYTES + vd2 * VT_PITCH + vc * 16) = st[4]; } while (0)
; __device__ __forceinline__ void attn_unit(KParams& P, int l, const AUnit& U, LAS unsigned char* lds) {
;     ...
;         for (int s = 0; s < 10; ++s) {
;             const bf16x8 k0 = *(const LAS bf16x8*)(bb + koff + 32 * s), k1 = *(const LAS bf16x8*)(bb + koff + 32 * KT_PITCH + 32 * s);
;             p0 = __builtin_amdgcn_mfma_f32_32x32x16_bf16(k0, qf[s], p0, 0, 0, 0);
;             p1 = __builtin_amdgcn_mfma_f32_32x32x16_bf16(k1, qf[s], p1, 0, 0, 0);
;         }
;     ...
;         for (int d = 0; d < 4; ++d)
; #pragma unroll
;             for (int ks = 0; ks < 4; ++ks) {
;                 const bf16x8 vf = *(const LAS bf16x8*)(bb + voff + d * 32 * VT_PITCH + 32 * ks);
;                 o[d] = __builtin_amdgcn_mfma_f32_32x32x16_bf16(vf, pf[ks], o[d], 0, 0, 0);
;             }
;         if (more) A_STORE((t + 1) & 1);
	v_add3_u32 v230, s23, v187, v156
	s_waitcnt lgkmcnt(5)
	v_mfma_f32_32x32x16_bf16 v[48:63], v[192:195], v[80:83], v[48:63]
	ds_read_b128 v[248:251], v231 offset:26176
	s_waitcnt lgkmcnt(5)
	v_mfma_f32_32x32x16_bf16 v[48:63], v[196:199], v[84:87], v[48:63]
	ds_read_b128 v[192:195], v231 offset:26208
	s_waitcnt lgkmcnt(5)
	v_mfma_f32_32x32x16_bf16 v[48:63], v[200:203], v[64:67], v[48:63]
	ds_read_b128 v[196:199], v231 offset:30720
	s_waitcnt lgkmcnt(5)
	v_mfma_f32_32x32x16_bf16 v[48:63], v[204:207], v[68:71], v[48:63]
	ds_read_b128 v[200:203], v231 offset:30752
	s_waitcnt lgkmcnt(5)
	v_mfma_f32_32x32x16_bf16 v[32:47], v[208:211], v[80:83], v[32:47]
	ds_read_b128 v[204:207], v231 offset:30784
	s_waitcnt lgkmcnt(5)
	v_mfma_f32_32x32x16_bf16 v[32:47], v[226:229], v[84:87], v[32:47]
	ds_read_b128 v[208:211], v231 offset:30816
	s_waitcnt lgkmcnt(5)
	v_mfma_f32_32x32x16_bf16 v[32:47], v[248:251], v[64:67], v[32:47]
	ds_read_b128 v[226:229], v231 offset:35328
	s_waitcnt lgkmcnt(5)
	v_mfma_f32_32x32x16_bf16 v[32:47], v[192:195], v[68:71], v[32:47]
	ds_read_b128 v[248:251], v231 offset:35360
	s_waitcnt lgkmcnt(5)
	v_mfma_f32_32x32x16_bf16 v[16:31], v[196:199], v[80:83], v[16:31]
	ds_read_b128 v[192:195], v231 offset:35392
	s_waitcnt lgkmcnt(5)
	v_mfma_f32_32x32x16_bf16 v[16:31], v[200:203], v[84:87], v[16:31]
	ds_read_b128 v[196:199], v231 offset:35424
	s_waitcnt lgkmcnt(5)
	v_mfma_f32_32x32x16_bf16 v[16:31], v[204:207], v[64:67], v[16:31]
	ds_read_b128 v[200:203], v230
	s_waitcnt lgkmcnt(5)
	v_mfma_f32_32x32x16_bf16 v[16:31], v[208:211], v[68:71], v[16:31]
	ds_read_b128 v[204:207], v230 offset:10752
	s_waitcnt lgkmcnt(5)
	v_mfma_f32_32x32x16_bf16 v[0:15], v[226:229], v[80:83], v[0:15]
	ds_read_b128 v[208:211], v230 offset:32
	s_waitcnt lgkmcnt(5)
	v_mfma_f32_32x32x16_bf16 v[0:15], v[248:251], v[84:87], v[0:15]
	ds_read_b128 v[226:229], v230 offset:10784
	s_waitcnt lgkmcnt(5)
	v_mfma_f32_32x32x16_bf16 v[0:15], v[192:195], v[64:67], v[0:15]
	ds_read_b128 v[248:251], v230 offset:64
	s_waitcnt lgkmcnt(5)
	v_mfma_f32_32x32x16_bf16 v[0:15], v[196:199], v[68:71], v[0:15]
	ds_read_b128 v[192:195], v230 offset:10816
	s_waitcnt lgkmcnt(5)
	v_mfma_f32_32x32x16_bf16 v[80:95], v[200:203], v[96:99], v[232:247]
	ds_read_b128 v[196:199], v230 offset:96
	s_waitcnt lgkmcnt(5)
	v_mfma_f32_32x32x16_bf16 v[64:79], v[204:207], v[96:99], v[232:247]
	ds_read_b128 v[200:203], v230 offset:10848
	s_waitcnt lgkmcnt(5)
	v_mfma_f32_32x32x16_bf16 v[80:95], v[208:211], v[100:103], v[80:95]
	ds_read_b128 v[204:207], v230 offset:128
	s_waitcnt lgkmcnt(5)
	v_mfma_f32_32x32x16_bf16 v[64:79], v[226:229], v[100:103], v[64:79]
	ds_read_b128 v[208:211], v230 offset:10880
	s_waitcnt lgkmcnt(5)
	v_mfma_f32_32x32x16_bf16 v[80:95], v[248:251], v[104:107], v[80:95]
	ds_read_b128 v[226:229], v230 offset:160
	s_waitcnt lgkmcnt(5)
	v_mfma_f32_32x32x16_bf16 v[64:79], v[192:195], v[104:107], v[64:79]
	ds_read_b128 v[248:251], v230 offset:10912
	s_waitcnt lgkmcnt(5)
	v_mfma_f32_32x32x16_bf16 v[80:95], v[196:199], v[108:111], v[80:95]
	ds_read_b128 v[192:195], v230 offset:192
	s_waitcnt lgkmcnt(5)
	v_mfma_f32_32x32x16_bf16 v[64:79], v[200:203], v[108:111], v[64:79]
	ds_read_b128 v[196:199], v230 offset:10944
	s_waitcnt lgkmcnt(5)
	v_mfma_f32_32x32x16_bf16 v[80:95], v[204:207], v[112:115], v[80:95]
	ds_read_b128 v[200:203], v230 offset:224
	s_waitcnt lgkmcnt(5)
	v_mfma_f32_32x32x16_bf16 v[64:79], v[208:211], v[112:115], v[64:79]
	ds_read_b128 v[204:207], v230 offset:10976
	s_waitcnt lgkmcnt(5)
	v_mfma_f32_32x32x16_bf16 v[80:95], v[226:229], v[116:119], v[80:95]
	ds_read_b128 v[208:211], v230 offset:256
	s_waitcnt lgkmcnt(5)
	v_mfma_f32_32x32x16_bf16 v[64:79], v[248:251], v[116:119], v[64:79]
	ds_read_b128 v[226:229], v230 offset:11008
	s_waitcnt lgkmcnt(5)
	v_mfma_f32_32x32x16_bf16 v[80:95], v[192:195], v[120:123], v[80:95]
	ds_read_b128 v[248:251], v230 offset:288
	s_waitcnt lgkmcnt(5)
	v_mfma_f32_32x32x16_bf16 v[64:79], v[196:199], v[120:123], v[64:79]
	ds_read_b128 v[192:195], v230 offset:11040
	s_waitcnt lgkmcnt(5)
	v_mfma_f32_32x32x16_bf16 v[80:95], v[200:203], v[124:127], v[80:95]
	s_waitcnt lgkmcnt(4)
	v_mfma_f32_32x32x16_bf16 v[64:79], v[204:207], v[124:127], v[64:79]
	s_waitcnt lgkmcnt(3)
	v_mfma_f32_32x32x16_bf16 v[80:95], v[208:211], v[128:131], v[80:95]
	s_waitcnt lgkmcnt(2)
	v_mfma_f32_32x32x16_bf16 v[64:79], v[226:229], v[128:131], v[64:79]
	s_waitcnt lgkmcnt(1)
	v_mfma_f32_32x32x16_bf16 v[80:95], v[248:251], v[132:135], v[80:95]
	s_waitcnt lgkmcnt(0)
	v_mfma_f32_32x32x16_bf16 v[64:79], v[192:195], v[132:135], v[64:79]
	s_waitcnt lgkmcnt(0)
	s_mov_b32 s25, s22
	s_mov_b32 s22, s23
	s_mov_b32 s23, s24
	s_mov_b32 s24, s25
	s_add_i32 s20, s20, 1
	s_branch .Lattn_loop
.Lattn_xlast:
	s_waitcnt lgkmcnt(5)
	v_mfma_f32_32x32x16_bf16 v[48:63], v[192:195], v[80:83], v[48:63]
	ds_read_b128 v[248:251], v231 offset:26176
	s_waitcnt lgkmcnt(5)
	v_mfma_f32_32x32x16_bf16 v[48:63], v[196:199], v[84:87], v[48:63]
	ds_read_b128 v[192:195], v231 offset:26208
	s_waitcnt lgkmcnt(5)
	v_mfma_f32_32x32x16_bf16 v[48:63], v[200:203], v[64:67], v[48:63]
	ds_read_b128 v[196:199], v231 offset:30720
	s_waitcnt lgkmcnt(5)
	v_mfma_f32_32x32x16_bf16 v[48:63], v[204:207], v[68:71], v[48:63]
	ds_read_b128 v[200:203], v231 offset:30752
	s_waitcnt lgkmcnt(5)
	v_mfma_f32_32x32x16_bf16 v[32:47], v[208:211], v[80:83], v[32:47]
	ds_read_b128 v[204:207], v231 offset:30784
	s_waitcnt lgkmcnt(5)
	v_mfma_f32_32x32x16_bf16 v[32:47], v[226:229], v[84:87], v[32:47]
	ds_read_b128 v[208:211], v231 offset:30816
	s_waitcnt lgkmcnt(5)
	v_mfma_f32_32x32x16_bf16 v[32:47], v[248:251], v[64:67], v[32:47]
	ds_read_b128 v[226:229], v231 offset:35328
	s_waitcnt lgkmcnt(5)
	v_mfma_f32_32x32x16_bf16 v[32:47], v[192:195], v[68:71], v[32:47]
	ds_read_b128 v[248:251], v231 offset:35360
	s_waitcnt lgkmcnt(5)
	v_mfma_f32_32x32x16_bf16 v[16:31], v[196:199], v[80:83], v[16:31]
	ds_read_b128 v[192:195], v231 offset:35392
	s_waitcnt lgkmcnt(5)
	v_mfma_f32_32x32x16_bf16 v[16:31], v[200:203], v[84:87], v[16:31]
	ds_read_b128 v[196:199], v231 offset:35424
	s_waitcnt lgkmcnt(5)
	v_mfma_f32_32x32x16_bf16 v[16:31], v[204:207], v[64:67], v[16:31]
	s_waitcnt lgkmcnt(4)
	v_mfma_f32_32x32x16_bf16 v[16:31], v[208:211], v[68:71], v[16:31]
	s_waitcnt lgkmcnt(3)
	v_mfma_f32_32x32x16_bf16 v[0:15], v[226:229], v[80:83], v[0:15]
	s_waitcnt lgkmcnt(2)
	v_mfma_f32_32x32x16_bf16 v[0:15], v[248:251], v[84:87], v[0:15]
	s_waitcnt lgkmcnt(1)
	v_mfma_f32_32x32x16_bf16 v[0:15], v[192:195], v[64:67], v[0:15]
	s_waitcnt lgkmcnt(0)
	v_mfma_f32_32x32x16_bf16 v[0:15], v[196:199], v[68:71], v[0:15]
	s_waitcnt lgkmcnt(0)
	s_cmp_lt_u32 s88, 4
	s_cbranch_scc0 .Lattn_done
	s_barrier
